# NSA sel/window loops: rare mask and rescale blocks moved out of line so the common path falls through (fewer taken branches); on top of v33
# speedup vs baseline: 1.0077x; 1.0077x over previous
; DI void tile_scores(f32x16& x0, f32x16& x1, const LAS unsigned char* buf, const bf16x8 (&qf)[4], float sk, float aref, int p0, bool laneok, bool needmask, int lo, int hip, int r32, int hi) {
;     KFrag K0, K1; lds_k(K0, buf, 0, r32, hi); lds_k(K1, buf, 1, r32, hi);
;     const float B = laneok ? fmaf(sk, (float)(p0 + 4 * hi), -aref) : -1e30f;
;     const float B1 = B + 32.f * sk;
; #pragma unroll
;     for (int r = 0; r < 16; ++r) { x0[r] = fmaf(sk, (float)ccol(r), B); x1[r] = fmaf(sk, (float)ccol(r), B1); }
; #pragma unroll
;     for (int d0 = 0; d0 < 4; ++d0) { x0 = MFMA32(K0.k[d0], qf[d0], x0); x1 = MFMA32(K1.k[d0], qf[d0], x1); }
;     if (needmask) {
; #pragma unroll
;         for (int r = 0; r < 16; ++r) { const int pos = p0 + crow(r, hi); if (pos < lo || pos > hip) x0[r] = -1e30f; if (pos + 32 < lo || pos + 32 > hip) x1[r] = -1e30f; }
;     }
; }
; DI float soft_update(Soft& f, f32x16& x0, f32x16& x1, bool hasO) {
;     float ma = fmaxf(fmaxf(x0[0], x1[0]), x0[1]), mb = fmaxf(fmaxf(x1[1], x0[2]), x1[2]);
; #pragma unroll
;     for (int r = 3; r < 15; r += 2) { ma = fmaxf(fmaxf(ma, x0[r]), x1[r]); mb = fmaxf(fmaxf(mb, x0[r + 1]), x1[r + 1]); }
;     ma = fmaxf(fmaxf(ma, x0[15]), x1[15]);
;     float mx = xhalf_max(fmaxf(ma, mb));
;     const bool valid = mx > -1e20f;
;     const bool need = valid && (mx > 8.f || !f.seen);
;     float dmove = 0.f;
;     if (__builtin_amdgcn_ballot_w64(need)) {
;         const float delta = need ? fmaxf(mx, -60.f) : 0.f; const float sc = fast_exp2(-delta);
; DI void nsa_unit(const bf16* PR, const bf16* VT, const bf16* kcb, const bf16* vctb, bf16* Y, LAS unsigned char* lds, int b, int g, int jt) {
;     ...
;             const LAS unsigned char* buf = tb + par * TBUF;
;             const int jw = jcur >> 5, jb = jcur & 31;
;             const unsigned wuw = jw == 0 ? wu0 : (jw == 1 ? wu1 : (jw == 2 ? wu2 : wu3));
;             if ((wuw >> jb) & 1u) {
;                 const unsigned mw = jw == 0 ? mk0 : (jw == 1 ? mk1 : (jw == 2 ? mk2 : mk3));
;                 const bool mysel = (mw >> jb) & 1u;
;                 VFrag V0, V1; lds_v(V0, buf, 0, r32, hi); lds_v(V1, buf, 1, r32, hi);
;                 f32x16 x0, x1; tile_scores(x0, x1, buf, qf, slope2, ab + f.mref, 64 * jcur, mysel, jcur == jt, -(1 << 30), t, r32, hi);
;                 soft_update(f, x0, x1, true);
;                 tile_pv2(f, V0, V1, x0, x1);
.LBB0_996:
	s_lshr_b32 s8, s10, 5
	s_cmp_eq_u32 s8, 2
	s_cselect_b64 vcc, -1, 0
	s_and_b64 s[6:7], vcc, exec
	s_cselect_b32 s11, s50, s52
	s_cmp_eq_u32 s8, 1
	s_cselect_b64 s[6:7], -1, 0
	s_and_b64 s[8:9], s[6:7], exec
	s_cselect_b32 s11, s48, s11
	s_cmp_lt_u32 s10, 32
	s_cselect_b64 s[8:9], -1, 0
	s_and_b64 s[12:13], s[8:9], exec
	s_cselect_b32 s12, s46, s11
	s_lshl_b32 s11, 1, s10
	s_and_b32 s12, s12, s11
	s_cmp_eq_u32 s12, 0
	s_cbranch_scc1 .LBB0_1008
	v_cndmask_b32_e32 v1, v115, v114, vcc
	v_cndmask_b32_e64 v1, v1, v113, s[6:7]
	v_cndmask_b32_e64 v1, v1, v112, s[8:9]
	v_and_b32_e32 v14, s11, v1
	v_lshl_or_b32 v1, s10, 6, v240
	v_cvt_f32_u32_e32 v80, v1
	s_mul_i32 s12, s2, 0x4600
	s_add_i32 s12, s12, 0
	v_add_f32_e32 v15, v247, v167
	v_add3_u32 v128, s12, v245, v206
	v_fma_f32 v15, v208, v80, -v15
	v_cmp_ne_u32_e32 vcc, 0, v14
	ds_read_b128 v[2:5], v128
	ds_read_b128 v[6:9], v128 offset:32
	ds_read_b128 v[10:13], v128 offset:4608
	ds_read_b128 v[124:127], v128 offset:4640
	v_cndmask_b32_e32 v14, v222, v15, vcc
	v_fma_f32 v96, 0, v208, v14
	v_add_f32_e32 v97, v208, v14
	v_pk_fma_f32 v[98:99], v[208:209], s[82:83], v[14:15] op_sel_hi:[1,1,0]
	v_pk_fma_f32 v[100:101], v[208:209], s[84:85], v[14:15] op_sel_hi:[1,1,0]
	v_pk_fma_f32 v[102:103], v[208:209], s[86:87], v[14:15] op_sel_hi:[1,1,0]
	v_pk_fma_f32 v[104:105], v[208:209], s[80:81], v[14:15] op_sel_hi:[1,1,0]
	v_pk_fma_f32 v[106:107], v[208:209], s[88:89], v[14:15] op_sel_hi:[1,1,0]
	v_pk_fma_f32 v[108:109], v[208:209], s[90:91], v[14:15] op_sel_hi:[1,1,0]
	v_pk_fma_f32 v[110:111], v[208:209], s[92:93], v[14:15] op_sel_hi:[1,1,0]
	v_add_f32_e32 v94, v166, v14
	v_fma_f32 v80, 0, v208, v94
	s_waitcnt lgkmcnt(3)
	v_mfma_f32_32x32x16_bf16 v[96:111], v[2:5], v[144:147], v[96:111]
	v_add_f32_e32 v81, v208, v94
	v_fma_f32 v82, v208, s82, v94
	v_fma_f32 v83, v209, s83, v94
	v_fma_f32 v84, v208, s84, v94
	v_fma_f32 v85, v209, s85, v94
	v_pk_fma_f32 v[86:87], v[208:209], s[86:87], v[94:95] op_sel_hi:[1,1,0]
	v_pk_fma_f32 v[88:89], v[208:209], s[80:81], v[94:95] op_sel_hi:[1,1,0]
	v_pk_fma_f32 v[90:91], v[208:209], s[88:89], v[94:95] op_sel_hi:[1,1,0]
	v_pk_fma_f32 v[92:93], v[208:209], s[90:91], v[94:95] op_sel_hi:[1,1,0]
	v_pk_fma_f32 v[94:95], v[208:209], s[92:93], v[94:95] op_sel_hi:[1,1,0]
	s_waitcnt lgkmcnt(2)
	v_mfma_f32_32x32x16_bf16 v[96:111], v[6:9], v[148:151], v[96:111]
	ds_read_b128 v[2:5], v128 offset:64
	ds_read_b128 v[6:9], v128 offset:96
	s_cmp_lg_u32 s10, s72
	s_waitcnt lgkmcnt(3)
	v_mfma_f32_32x32x16_bf16 v[80:95], v[10:13], v[144:147], v[80:95]
	s_waitcnt lgkmcnt(2)
	v_mfma_f32_32x32x16_bf16 v[80:95], v[124:127], v[148:151], v[80:95]
	s_waitcnt lgkmcnt(1)
	v_mfma_f32_32x32x16_bf16 v[96:111], v[2:5], v[152:155], v[96:111]
	ds_read_b128 v[2:5], v128 offset:4672
	ds_read_b128 v[174:177], v128 offset:4704
	s_waitcnt lgkmcnt(1)
	v_mfma_f32_32x32x16_bf16 v[80:95], v[2:5], v[152:155], v[80:95]
	v_add3_u32 v2, s12, v207, v244
	v_add_u32_e32 v3, 0x2000, v2
	v_add_u32_e32 v2, 0x3000, v2
	ds_read_b64 v[140:141], v3 offset:1024
	ds_read_b64 v[142:143], v3 offset:1040
	ds_read_b64 v[132:133], v3 offset:1056
	ds_read_b64 v[134:135], v3 offset:1072
	v_mfma_f32_32x32x16_bf16 v[96:111], v[6:9], v[156:159], v[96:111]
	ds_read_b64 v[136:137], v2 offset:1280
	ds_read_b64 v[138:139], v2 offset:1296
	ds_read_b64 v[128:129], v2 offset:1312
	ds_read_b64 v[130:131], v2 offset:1328
	ds_read_b64 v[124:125], v3 offset:1088
	ds_read_b64 v[126:127], v3 offset:1104
	ds_read_b64 v[10:11], v2 offset:1344
	ds_read_b64 v[12:13], v2 offset:1360
	ds_read_b64 v[6:7], v3 offset:1120
	ds_read_b64 v[8:9], v3 offset:1136
	ds_read_b64 v[4:5], v2 offset:1392
	ds_read_b64 v[2:3], v2 offset:1376
	s_waitcnt lgkmcnt(15)
	v_mfma_f32_32x32x16_bf16 v[80:95], v[174:177], v[156:159], v[80:95]
	s_cbranch_scc0 .Lsel_mask
.LBB0_1001:
	s_nop 10
	v_max_f32_e32 v1, v80, v80
	v_max_f32_e32 v14, v96, v96
	v_max_f32_e32 v1, v14, v1
	v_max3_f32 v14, v81, v98, v82
	v_max3_f32 v1, v1, v97, v99
	v_max3_f32 v14, v14, v100, v84
	v_max3_f32 v1, v1, v83, v101
	v_max3_f32 v14, v14, v102, v86
	v_max3_f32 v1, v1, v85, v103
	v_max3_f32 v14, v14, v104, v88
	v_max3_f32 v1, v1, v87, v105
	v_max3_f32 v14, v14, v106, v90
	v_max3_f32 v1, v1, v89, v107
	v_max3_f32 v14, v14, v108, v92
	v_max3_f32 v1, v1, v91, v109
	v_max3_f32 v14, v14, v110, v94
	v_max3_f32 v1, v1, v93, v111
	v_max3_f32 v1, v1, v95, v14
	v_mov_b32_e32 v14, v1
	s_nop 1
	v_permlane32_swap_b32_e32 v1, v14
	v_max_f32_e32 v14, v14, v14
	v_max_f32_e32 v1, v1, v1
	v_max_f32_e32 v1, v1, v14
	v_cmp_lt_f32_e64 s[6:7], s70, v1
	v_cmp_lt_f32_e64 s[8:9], s84, v1
	s_orn2_b64 s[8:9], s[8:9], s[4:5]
	s_and_b64 s[8:9], s[8:9], s[6:7]
	s_cbranch_scc1 .Lsel_resc

; DI float fast_exp2(float x) { return __builtin_amdgcn_exp2f(x); }
; DI int crow(int r, int hi) { return (r & 3) + 8 * (r >> 2) + 4 * hi; }
; DI void tile_scores(f32x16& x0, f32x16& x1, const LAS unsigned char* buf, const bf16x8 (&qf)[4], float sk, float aref, int p0, bool laneok, bool needmask, int lo, int hip, int r32, int hi) {
;     ...
;     if (needmask) {
; #pragma unroll
;         for (int r = 0; r < 16; ++r) { const int pos = p0 + crow(r, hi); if (pos < lo || pos > hip) x0[r] = -1e30f; if (pos + 32 < lo || pos + 32 > hip) x1[r] = -1e30f; }
;     }
; DI float soft_update(Soft& f, f32x16& x0, f32x16& x1, bool hasO) {
;     ...
;     if (__builtin_amdgcn_ballot_w64(need)) {
;         const float delta = need ? fmaxf(mx, -60.f) : 0.f; const float sc = fast_exp2(-delta);
;         dmove = delta;
;         f.mref += delta; f.l *= sc;
;         if (hasO) {
; #pragma unroll
;             for (int r = 0; r < 16; ++r) { f.o0[r] *= sc; f.o1[r] *= sc; } }
; #pragma unroll
;         for (int r = 0; r < 16; ++r) { x0[r] -= delta; x1[r] -= delta; }
;     }
.Lsel_mask:
	v_or_b32_e32 v14, 32, v1
	v_cmp_le_i32_e64 s[6:7], v14, v204
	v_or_b32_e32 v14, 33, v1
	v_cmp_le_i32_e64 s[8:9], v14, v204
	v_or_b32_e32 v14, 2, v1
	v_cmp_le_i32_e32 vcc, v1, v204
	s_nop 4
	v_cndmask_b32_e64 v81, v222, v81, s[8:9]
	v_cmp_le_i32_e64 s[8:9], v14, v204
	v_or_b32_e32 v14, 34, v1
	v_cmp_le_i32_e64 s[10:11], v14, v204
	v_or_b32_e32 v14, 3, v1
	v_cndmask_b32_e64 v80, v222, v80, s[6:7]
	v_cndmask_b32_e64 v82, v222, v82, s[10:11]
	v_cmp_le_i32_e64 s[10:11], v14, v204
	v_or_b32_e32 v14, 35, v1
	v_cmp_le_i32_e64 s[12:13], v14, v204
	v_or_b32_e32 v14, 8, v1
	v_cmp_lt_i32_e64 s[6:7], v1, v204
	v_cndmask_b32_e64 v83, v222, v83, s[12:13]
	v_cmp_le_i32_e64 s[12:13], v14, v204
	v_or_b32_e32 v14, 40, v1
	v_cmp_le_i32_e64 s[14:15], v14, v204
	v_or_b32_e32 v14, 9, v1
	s_nop 0
	v_cndmask_b32_e64 v84, v222, v84, s[14:15]
	v_cmp_le_i32_e64 s[14:15], v14, v204
	v_or_b32_e32 v14, 41, v1
	v_cmp_le_i32_e64 s[16:17], v14, v204
	v_or_b32_e32 v14, 10, v1
	s_nop 0
	v_cndmask_b32_e64 v85, v222, v85, s[16:17]
	v_cmp_le_i32_e64 s[16:17], v14, v204
	v_or_b32_e32 v14, 42, v1
	v_cmp_le_i32_e64 s[18:19], v14, v204
	v_or_b32_e32 v14, 11, v1
	s_nop 0
	v_cndmask_b32_e64 v86, v222, v86, s[18:19]
	v_cmp_le_i32_e64 s[18:19], v14, v204
	v_or_b32_e32 v14, 43, v1
	v_cmp_le_i32_e64 s[20:21], v14, v204
	v_or_b32_e32 v14, 16, v1
	s_nop 0
	v_cndmask_b32_e64 v87, v222, v87, s[20:21]
	v_cmp_le_i32_e64 s[20:21], v14, v204
	v_or_b32_e32 v14, 48, v1
	v_cmp_le_i32_e64 s[22:23], v14, v204
	v_or_b32_e32 v14, 17, v1
	s_nop 0
	v_cndmask_b32_e64 v88, v222, v88, s[22:23]
	v_cmp_le_i32_e64 s[22:23], v14, v204
	v_or_b32_e32 v14, 49, v1
	v_cmp_le_i32_e64 s[24:25], v14, v204
	v_or_b32_e32 v14, 18, v1
	s_nop 0
	v_cndmask_b32_e64 v89, v222, v89, s[24:25]
	v_cmp_le_i32_e64 s[24:25], v14, v204
	v_or_b32_e32 v14, 50, v1
	v_cmp_le_i32_e64 s[26:27], v14, v204
	v_or_b32_e32 v14, 19, v1
	s_nop 0
	v_cndmask_b32_e64 v90, v222, v90, s[26:27]
	v_cmp_le_i32_e64 s[26:27], v14, v204
	v_or_b32_e32 v14, 51, v1
	v_cmp_le_i32_e64 s[28:29], v14, v204
	v_or_b32_e32 v14, 24, v1
	s_nop 0
	v_cndmask_b32_e64 v91, v222, v91, s[28:29]
	v_cmp_le_i32_e64 s[28:29], v14, v204
	v_or_b32_e32 v14, 56, v1
	v_cmp_le_i32_e64 s[30:31], v14, v204
	v_or_b32_e32 v14, 25, v1
	s_nop 0
	v_cndmask_b32_e64 v92, v222, v92, s[30:31]
	v_cmp_le_i32_e64 s[30:31], v14, v204
	v_or_b32_e32 v14, 57, v1
	v_cmp_le_i32_e64 s[34:35], v14, v204
	v_or_b32_e32 v14, 26, v1
	s_nop 0
	v_cndmask_b32_e64 v93, v222, v93, s[34:35]
	v_cmp_le_i32_e64 s[34:35], v14, v204
	v_or_b32_e32 v14, 58, v1
	v_cmp_le_i32_e64 s[36:37], v14, v204
	v_or_b32_e32 v14, 27, v1
	v_or_b32_e32 v1, 59, v1
	v_cndmask_b32_e64 v94, v222, v94, s[36:37]
	v_cmp_le_i32_e64 s[36:37], v14, v204
	v_cmp_gt_i32_e64 s[38:39], v1, v204
	s_and_saveexec_b64 s[44:45], s[38:39]
	v_mov_b32_e32 v95, s75
	s_or_b64 exec, exec, s[44:45]
	v_cndmask_b32_e64 v97, v222, v97, s[6:7]
	v_cndmask_b32_e32 v96, v222, v96, vcc
	v_cndmask_b32_e64 v98, v222, v98, s[8:9]
	v_cndmask_b32_e64 v99, v222, v99, s[10:11]
	v_cndmask_b32_e64 v100, v222, v100, s[12:13]
	v_cndmask_b32_e64 v101, v222, v101, s[14:15]
	v_cndmask_b32_e64 v102, v222, v102, s[16:17]
	v_cndmask_b32_e64 v103, v222, v103, s[18:19]
	v_cndmask_b32_e64 v104, v222, v104, s[20:21]
	v_cndmask_b32_e64 v105, v222, v105, s[22:23]
	v_cndmask_b32_e64 v106, v222, v106, s[24:25]
	v_cndmask_b32_e64 v107, v222, v107, s[26:27]
	v_cndmask_b32_e64 v108, v222, v108, s[28:29]
	v_cndmask_b32_e64 v109, v222, v109, s[30:31]
	v_cndmask_b32_e64 v110, v222, v110, s[34:35]
	v_cndmask_b32_e64 v111, v222, v111, s[36:37]
	s_branch .LBB0_1001
.Lsel_resc:
	v_max_f32_e32 v1, v1, v1
	v_max_f32_e32 v1, 0xc2700000, v1
	v_cndmask_b32_e64 v14, 0, v1, s[8:9]
	v_exp_f32_e64 v174, -v14
	v_add_f32_e32 v167, v167, v14
	v_pk_add_f32 v[96:97], v[96:97], v[14:15] op_sel_hi:[1,0] neg_lo:[0,1] neg_hi:[0,1]
	v_pk_add_f32 v[80:81], v[80:81], v[14:15] op_sel_hi:[1,0] neg_lo:[0,1] neg_hi:[0,1]
	v_mul_f32_e32 v211, v211, v174
	v_pk_mul_f32 v[78:79], v[78:79], v[174:175] op_sel_hi:[1,0]
	v_pk_mul_f32 v[76:77], v[76:77], v[174:175] op_sel_hi:[1,0]
	v_pk_mul_f32 v[74:75], v[74:75], v[174:175] op_sel_hi:[1,0]
	v_pk_mul_f32 v[72:73], v[72:73], v[174:175] op_sel_hi:[1,0]
	v_pk_mul_f32 v[70:71], v[70:71], v[174:175] op_sel_hi:[1,0]
	v_pk_mul_f32 v[68:69], v[68:69], v[174:175] op_sel_hi:[1,0]
	v_pk_mul_f32 v[66:67], v[66:67], v[174:175] op_sel_hi:[1,0]
	v_pk_mul_f32 v[64:65], v[64:65], v[174:175] op_sel_hi:[1,0]
	v_pk_mul_f32 v[62:63], v[62:63], v[174:175] op_sel_hi:[1,0]
	v_pk_mul_f32 v[60:61], v[60:61], v[174:175] op_sel_hi:[1,0]
	v_pk_mul_f32 v[58:59], v[58:59], v[174:175] op_sel_hi:[1,0]
	v_pk_mul_f32 v[56:57], v[56:57], v[174:175] op_sel_hi:[1,0]
	v_pk_mul_f32 v[54:55], v[54:55], v[174:175] op_sel_hi:[1,0]
	v_pk_mul_f32 v[52:53], v[52:53], v[174:175] op_sel_hi:[1,0]
	v_pk_mul_f32 v[50:51], v[50:51], v[174:175] op_sel_hi:[1,0]
	v_pk_mul_f32 v[48:49], v[48:49], v[174:175] op_sel_hi:[1,0]
	v_pk_add_f32 v[98:99], v[98:99], v[14:15] op_sel_hi:[1,0] neg_lo:[0,1] neg_hi:[0,1]
	v_pk_add_f32 v[82:83], v[82:83], v[14:15] op_sel_hi:[1,0] neg_lo:[0,1] neg_hi:[0,1]
	v_pk_add_f32 v[100:101], v[100:101], v[14:15] op_sel_hi:[1,0] neg_lo:[0,1] neg_hi:[0,1]
	v_pk_add_f32 v[84:85], v[84:85], v[14:15] op_sel_hi:[1,0] neg_lo:[0,1] neg_hi:[0,1]
	v_pk_add_f32 v[102:103], v[102:103], v[14:15] op_sel_hi:[1,0] neg_lo:[0,1] neg_hi:[0,1]
	v_pk_add_f32 v[86:87], v[86:87], v[14:15] op_sel_hi:[1,0] neg_lo:[0,1] neg_hi:[0,1]
	v_pk_add_f32 v[104:105], v[104:105], v[14:15] op_sel_hi:[1,0] neg_lo:[0,1] neg_hi:[0,1]
	v_pk_add_f32 v[88:89], v[88:89], v[14:15] op_sel_hi:[1,0] neg_lo:[0,1] neg_hi:[0,1]
	v_pk_add_f32 v[106:107], v[106:107], v[14:15] op_sel_hi:[1,0] neg_lo:[0,1] neg_hi:[0,1]
	v_pk_add_f32 v[90:91], v[90:91], v[14:15] op_sel_hi:[1,0] neg_lo:[0,1] neg_hi:[0,1]
	v_pk_add_f32 v[108:109], v[108:109], v[14:15] op_sel_hi:[1,0] neg_lo:[0,1] neg_hi:[0,1]
	v_pk_add_f32 v[92:93], v[92:93], v[14:15] op_sel_hi:[1,0] neg_lo:[0,1] neg_hi:[0,1]
	v_pk_add_f32 v[110:111], v[110:111], v[14:15] op_sel_hi:[1,0] neg_lo:[0,1] neg_hi:[0,1]
	v_pk_add_f32 v[94:95], v[94:95], v[14:15] op_sel_hi:[1,0] neg_lo:[0,1] neg_hi:[0,1]
	s_branch .LBB0_1007

; #define LAS __attribute__((address_space(3)))
; #define MFMA32(a, b, c) __builtin_amdgcn_mfma_f32_32x32x16_bf16((a), (b), (c), 0, 0, 0)
; DI float xhalf_max(float v) { const auto rr = __builtin_amdgcn_permlane32_swap(__float_as_uint(v), __float_as_uint(v), false, false); return fmaxf(__uint_as_float(rr[0]), __uint_as_float(rr[1])); }
; DI int ccol(int r) { return (r & 3) + 8 * (r >> 2); }
; DI void tile_scores(f32x16& x0, f32x16& x1, const LAS unsigned char* buf, const bf16x8 (&qf)[4], float sk, float aref, int p0, bool laneok, bool needmask, int lo, int hip, int r32, int hi) {
;     KFrag K0, K1; lds_k(K0, buf, 0, r32, hi); lds_k(K1, buf, 1, r32, hi);
;     const float B = laneok ? fmaf(sk, (float)(p0 + 4 * hi), -aref) : -1e30f;
;     const float B1 = B + 32.f * sk;
; #pragma unroll
;     for (int r = 0; r < 16; ++r) { x0[r] = fmaf(sk, (float)ccol(r), B); x1[r] = fmaf(sk, (float)ccol(r), B1); }
; #pragma unroll
;     for (int d0 = 0; d0 < 4; ++d0) { x0 = MFMA32(K0.k[d0], qf[d0], x0); x1 = MFMA32(K1.k[d0], qf[d0], x1); }
; DI float soft_update(Soft& f, f32x16& x0, f32x16& x1, bool hasO) {
;     float ma = fmaxf(fmaxf(x0[0], x1[0]), x0[1]), mb = fmaxf(fmaxf(x1[1], x0[2]), x1[2]);
; #pragma unroll
;     for (int r = 3; r < 15; r += 2) { ma = fmaxf(fmaxf(ma, x0[r]), x1[r]); mb = fmaxf(fmaxf(mb, x0[r + 1]), x1[r + 1]); }
;     ma = fmaxf(fmaxf(ma, x0[15]), x1[15]);
;     float mx = xhalf_max(fmaxf(ma, mb));
;     const bool valid = mx > -1e20f;
;     const bool need = valid && (mx > 8.f || !f.seen);
;     float dmove = 0.f;
;     if (__builtin_amdgcn_ballot_w64(need)) {
; DI void nsa_unit(const bf16* PR, const bf16* VT, const bf16* kcb, const bf16* vctb, bf16* Y, LAS unsigned char* lds, int b, int g, int jt) {
;     ...
;         for (int kt = klast; kt >= kfirst; kt -= 64) {
;             if (kt - 64 >= kfirst) stage_load(R, kw + (size_t)(kt - 64) * 64, 64, vwt + kt - 64, SEQ, tid, true);
;             const LAS unsigned char* buf = tb + par * TBUF;
;             if (kt + 63 >= tw0 - 511) {
;                 const bool needmask = (kt + 63 > tw0) || (kt < tw0 + 31 - 511);
;                 VFrag V0, V1; lds_v(V0, buf, 0, r32, hi); lds_v(V1, buf, 1, r32, hi);
;                 f32x16 x0, x1; tile_scores(x0, x1, buf, qf, slope2, ab + f.mref, kt, true, needmask, t - 511, t, r32, hi);
;                 soft_update(f, x0, x1, true);
.LBB0_1020:
	v_add_u32_e32 v14, s94, v240
	v_add_u32_e32 v15, 64, v14
	v_cvt_f32_u32_e32 v113, v15
	s_mul_i32 s7, s1, 0x4600
	s_add_i32 s10, s7, 0
	v_add_f32_e32 v112, v247, v1
	v_add3_u32 v172, s10, v245, v206
	ds_read_b128 v[2:5], v172
	ds_read_b128 v[6:9], v172 offset:32
	ds_read_b128 v[10:13], v172 offset:4608
	ds_read_b128 v[168:171], v172 offset:4640
	v_fma_f32 v114, v208, v113, -v112
	v_fma_f32 v128, 0, v208, v114
	v_add_f32_e32 v129, v208, v114
	v_pk_fma_f32 v[130:131], v[208:209], s[82:83], v[114:115] op_sel_hi:[1,1,0]
	v_pk_fma_f32 v[132:133], v[208:209], s[84:85], v[114:115] op_sel_hi:[1,1,0]
	v_pk_fma_f32 v[134:135], v[208:209], s[86:87], v[114:115] op_sel_hi:[1,1,0]
	v_pk_fma_f32 v[136:137], v[208:209], s[80:81], v[114:115] op_sel_hi:[1,1,0]
	v_pk_fma_f32 v[138:139], v[208:209], s[88:89], v[114:115] op_sel_hi:[1,1,0]
	v_pk_fma_f32 v[140:141], v[208:209], s[90:91], v[114:115] op_sel_hi:[1,1,0]
	v_pk_fma_f32 v[142:143], v[208:209], s[92:93], v[114:115] op_sel_hi:[1,1,0]
	v_add_f32_e32 v126, v248, v114
	v_fma_f32 v112, 0, v208, v126
	s_waitcnt lgkmcnt(3)
	v_mfma_f32_32x32x16_bf16 v[128:143], v[2:5], v[144:147], v[128:143]
	v_add_f32_e32 v113, v208, v126
	v_fma_f32 v114, v208, s82, v126
	v_fma_f32 v115, v209, s83, v126
	v_fma_f32 v116, v208, s84, v126
	v_fma_f32 v117, v209, s85, v126
	v_pk_fma_f32 v[118:119], v[208:209], s[86:87], v[126:127] op_sel_hi:[1,1,0]
	v_pk_fma_f32 v[120:121], v[208:209], s[80:81], v[126:127] op_sel_hi:[1,1,0]
	v_pk_fma_f32 v[122:123], v[208:209], s[88:89], v[126:127] op_sel_hi:[1,1,0]
	v_pk_fma_f32 v[124:125], v[208:209], s[90:91], v[126:127] op_sel_hi:[1,1,0]
	v_pk_fma_f32 v[126:127], v[208:209], s[92:93], v[126:127] op_sel_hi:[1,1,0]
	s_waitcnt lgkmcnt(2)
	v_mfma_f32_32x32x16_bf16 v[128:143], v[6:9], v[148:151], v[128:143]
	ds_read_b128 v[2:5], v172 offset:64
	ds_read_b128 v[6:9], v172 offset:96
	ds_read_b128 v[250:253], v172 offset:4704
	s_cmp_gt_i32 s6, s71
	s_cselect_b64 s[6:7], -1, 0
	s_cmp_lt_i32 s78, s0
	s_cselect_b64 s[8:9], -1, 0
	s_or_b64 s[6:7], s[6:7], s[8:9]
	s_waitcnt lgkmcnt(4)
	v_mfma_f32_32x32x16_bf16 v[112:127], v[10:13], v[144:147], v[112:127]
	v_add3_u32 v10, s10, v207, v244
	s_andn2_b64 vcc, exec, s[6:7]
	s_waitcnt lgkmcnt(2)
	v_mfma_f32_32x32x16_bf16 v[128:143], v[2:5], v[152:155], v[128:143]
	ds_read_b128 v[2:5], v172 offset:4672
	v_mfma_f32_32x32x16_bf16 v[112:127], v[168:171], v[148:151], v[112:127]
	s_waitcnt lgkmcnt(0)
	v_mfma_f32_32x32x16_bf16 v[112:127], v[2:5], v[152:155], v[112:127]
	v_add_u32_e32 v2, 0x2000, v10
	v_add_u32_e32 v3, 0x3000, v10
	ds_read_b64 v[184:185], v2 offset:1024
	ds_read_b64 v[186:187], v2 offset:1040
	ds_read_b64 v[176:177], v2 offset:1056
	ds_read_b64 v[178:179], v2 offset:1072
	ds_read_b64 v[180:181], v3 offset:1280
	ds_read_b64 v[182:183], v3 offset:1296
	ds_read_b64 v[172:173], v3 offset:1312
	ds_read_b64 v[174:175], v3 offset:1328
	ds_read_b64 v[168:169], v2 offset:1088
	ds_read_b64 v[170:171], v2 offset:1104
	v_mfma_f32_32x32x16_bf16 v[128:143], v[6:9], v[156:159], v[128:143]
	ds_read_b64 v[10:11], v3 offset:1344
	ds_read_b64 v[12:13], v3 offset:1360
	ds_read_b64 v[6:7], v2 offset:1120
	ds_read_b64 v[8:9], v2 offset:1136
	ds_read_b64 v[4:5], v3 offset:1392
	ds_read_b64 v[2:3], v3 offset:1376
	v_mfma_f32_32x32x16_bf16 v[112:127], v[250:253], v[156:159], v[112:127]
	s_cbranch_vccz .Lwin_mask
.LBB0_1024:
	s_nop 10
	v_max_f32_e32 v14, v112, v112
	v_max_f32_e32 v15, v128, v128
	v_max_f32_e32 v14, v15, v14
	v_max3_f32 v15, v113, v130, v114
	v_max3_f32 v14, v14, v129, v131
	v_max3_f32 v15, v15, v132, v116
	v_max3_f32 v14, v14, v115, v133
	v_max3_f32 v15, v15, v134, v118
	v_max3_f32 v14, v14, v117, v135
	v_max3_f32 v15, v15, v136, v120
	v_max3_f32 v14, v14, v119, v137
	v_max3_f32 v15, v15, v138, v122
	v_max3_f32 v14, v14, v121, v139
	v_max3_f32 v15, v15, v140, v124
	v_max3_f32 v14, v14, v123, v141
	v_max3_f32 v15, v15, v142, v126
	v_max3_f32 v14, v14, v125, v143
	v_max3_f32 v14, v14, v127, v15
	v_mov_b32_e32 v15, v14
	s_nop 1
	v_permlane32_swap_b32_e32 v14, v15
	v_max_f32_e32 v15, v15, v15
	v_max_f32_e32 v14, v14, v14
	v_max_f32_e32 v14, v14, v15
	v_cmp_lt_f32_e64 s[6:7], s70, v14
	v_cmp_lt_f32_e64 s[8:9], s84, v14
	s_orn2_b64 s[8:9], s[8:9], s[4:5]
	s_and_b64 s[8:9], s[8:9], s[6:7]
	s_cbranch_scc1 .Lwin_resc

; DI int crow(int r, int hi) { return (r & 3) + 8 * (r >> 2) + 4 * hi; }
; DI void tile_scores(f32x16& x0, f32x16& x1, const LAS unsigned char* buf, const bf16x8 (&qf)[4], float sk, float aref, int p0, bool laneok, bool needmask, int lo, int hip, int r32, int hi) {
;     ...
;     if (needmask) {
; #pragma unroll
;         for (int r = 0; r < 16; ++r) { const int pos = p0 + crow(r, hi); if (pos < lo || pos > hip) x0[r] = -1e30f; if (pos + 32 < lo || pos + 32 > hip) x1[r] = -1e30f; }
;     }
; DI void nsa_unit(const bf16* PR, const bf16* VT, const bf16* kcb, const bf16* vctb, bf16* Y, LAS unsigned char* lds, int b, int g, int jt) {
;     ...
;                 const bool needmask = (kt + 63 > tw0) || (kt < tw0 + 31 - 511);
;                 VFrag V0, V1; lds_v(V0, buf, 0, r32, hi); lds_v(V1, buf, 1, r32, hi);
;                 f32x16 x0, x1; tile_scores(x0, x1, buf, qf, slope2, ab + f.mref, kt, true, needmask, t - 511, t, r32, hi);
.Lwin_mask:
	v_add_u32_e32 v250, 0x60, v14
	v_cmp_lt_i32_e64 s[8:9], v250, v249
	v_cmp_gt_i32_e64 s[10:11], v250, v204
	v_cmp_lt_i32_e32 vcc, v15, v249
	v_cmp_gt_i32_e64 s[6:7], v15, v204
	s_or_b64 s[8:9], s[8:9], s[10:11]
	v_cmp_ge_i32_e64 s[10:11], v15, v204
	v_add_u32_e32 v15, 0x61, v14
	v_cmp_lt_i32_e64 s[12:13], v15, v249
	v_cmp_gt_i32_e64 s[14:15], v15, v204
	s_or_b64 s[12:13], s[12:13], s[14:15]
	v_add_u32_e32 v15, 0x42, v14
	v_cndmask_b32_e64 v113, v113, v222, s[12:13]
	v_cmp_lt_i32_e64 s[12:13], v15, v249
	v_cmp_gt_i32_e64 s[14:15], v15, v204
	v_add_u32_e32 v15, 0x62, v14
	v_cmp_lt_i32_e64 s[16:17], v15, v249
	v_cmp_gt_i32_e64 s[18:19], v15, v204
	s_or_b64 s[16:17], s[16:17], s[18:19]
	v_add_u32_e32 v15, 0x43, v14
	v_cndmask_b32_e64 v114, v114, v222, s[16:17]
	v_cmp_lt_i32_e64 s[16:17], v15, v249
	v_cmp_gt_i32_e64 s[18:19], v15, v204
	v_add_u32_e32 v15, 0x63, v14
	v_cmp_lt_i32_e64 s[20:21], v15, v249
	v_cmp_gt_i32_e64 s[22:23], v15, v204
	s_or_b64 s[20:21], s[20:21], s[22:23]
	v_add_u32_e32 v15, 0x48, v14
	v_cndmask_b32_e64 v115, v115, v222, s[20:21]
	v_cmp_lt_i32_e64 s[20:21], v15, v249
	v_cmp_gt_i32_e64 s[22:23], v15, v204
	v_add_u32_e32 v15, 0x68, v14
	v_cmp_lt_i32_e64 s[24:25], v15, v249
	v_cmp_gt_i32_e64 s[26:27], v15, v204
	s_or_b64 s[24:25], s[24:25], s[26:27]
	v_add_u32_e32 v15, 0x49, v14
	v_cndmask_b32_e64 v116, v116, v222, s[24:25]
	v_cmp_lt_i32_e64 s[24:25], v15, v249
	v_cmp_gt_i32_e64 s[26:27], v15, v204
	v_add_u32_e32 v15, 0x69, v14
	v_cmp_lt_i32_e64 s[28:29], v15, v249
	v_cmp_gt_i32_e64 s[30:31], v15, v204
	s_or_b64 s[28:29], s[28:29], s[30:31]
	v_add_u32_e32 v15, 0x4a, v14
	v_cndmask_b32_e64 v117, v117, v222, s[28:29]
	v_cmp_lt_i32_e64 s[28:29], v15, v249
	v_cmp_gt_i32_e64 s[30:31], v15, v204
	v_add_u32_e32 v15, 0x6a, v14
	v_cmp_lt_i32_e64 s[34:35], v15, v249
	v_cmp_gt_i32_e64 s[36:37], v15, v204
	s_or_b64 s[34:35], s[34:35], s[36:37]
	v_add_u32_e32 v15, 0x4b, v14
	v_cndmask_b32_e64 v118, v118, v222, s[34:35]
	v_cmp_lt_i32_e64 s[34:35], v15, v249
	v_cmp_gt_i32_e64 s[36:37], v15, v204
	v_add_u32_e32 v15, 0x6b, v14
	v_cmp_lt_i32_e64 s[38:39], v15, v249
	v_cmp_gt_i32_e64 s[40:41], v15, v204
	s_or_b64 s[38:39], s[38:39], s[40:41]
	v_add_u32_e32 v15, 0x50, v14
	v_cndmask_b32_e64 v119, v119, v222, s[38:39]
	v_cmp_lt_i32_e64 s[38:39], v15, v249
	v_cmp_gt_i32_e64 s[40:41], v15, v204
	v_add_u32_e32 v15, 0x70, v14
	v_cmp_lt_i32_e64 s[42:43], v15, v249
	v_cmp_gt_i32_e64 s[44:45], v15, v204
	s_or_b64 s[42:43], s[42:43], s[44:45]
	v_add_u32_e32 v15, 0x51, v14
	v_cndmask_b32_e64 v120, v120, v222, s[42:43]
	v_cmp_lt_i32_e64 s[42:43], v15, v249
	v_cmp_gt_i32_e64 s[44:45], v15, v204
	v_add_u32_e32 v15, 0x71, v14
	v_cmp_lt_i32_e64 s[46:47], v15, v249
	v_cmp_gt_i32_e64 s[48:49], v15, v204
	s_or_b64 s[46:47], s[46:47], s[48:49]
	v_add_u32_e32 v15, 0x52, v14
	v_cndmask_b32_e64 v121, v121, v222, s[46:47]
	v_cmp_lt_i32_e64 s[46:47], v15, v249
	v_cmp_gt_i32_e64 s[48:49], v15, v204
	v_add_u32_e32 v15, 0x72, v14
	v_cmp_lt_i32_e64 s[50:51], v15, v249
	v_cmp_gt_i32_e64 s[52:53], v15, v204
	s_or_b64 s[50:51], s[50:51], s[52:53]
	v_add_u32_e32 v15, 0x53, v14
	v_cndmask_b32_e64 v122, v122, v222, s[50:51]
	v_cmp_lt_i32_e64 s[50:51], v15, v249
	v_cmp_gt_i32_e64 s[52:53], v15, v204
	v_add_u32_e32 v15, 0x73, v14
	v_cmp_lt_i32_e64 s[54:55], v15, v249
	v_cmp_gt_i32_e64 s[56:57], v15, v204
	s_or_b64 s[54:55], s[54:55], s[56:57]
	v_add_u32_e32 v15, 0x58, v14
	v_cndmask_b32_e64 v123, v123, v222, s[54:55]
	v_cmp_lt_i32_e64 s[54:55], v15, v249
	v_cmp_gt_i32_e64 s[56:57], v15, v204
	v_add_u32_e32 v15, 0x78, v14
	v_cmp_lt_i32_e64 s[58:59], v15, v249
	v_cmp_gt_i32_e64 s[60:61], v15, v204
	s_or_b64 s[58:59], s[58:59], s[60:61]
	v_add_u32_e32 v15, 0x59, v14
	v_cndmask_b32_e64 v124, v124, v222, s[58:59]
	v_cmp_lt_i32_e64 s[58:59], v15, v249
	v_cmp_gt_i32_e64 s[60:61], v15, v204
	v_add_u32_e32 v15, 0x79, v14
	v_cmp_lt_i32_e64 s[62:63], v15, v249
	v_cmp_gt_i32_e64 s[64:65], v15, v204
	s_or_b64 s[62:63], s[62:63], s[64:65]
	v_add_u32_e32 v15, 0x5a, v14
	v_cndmask_b32_e64 v125, v125, v222, s[62:63]
	v_cmp_lt_i32_e64 s[62:63], v15, v249
	v_cmp_gt_i32_e64 s[64:65], v15, v204
	v_add_u32_e32 v15, 0x7a, v14
	v_add_u32_e32 v250, 0x41, v14
	v_cmp_lt_i32_e64 s[66:67], v15, v249
	v_cmp_gt_i32_e64 s[68:69], v15, v204
	v_add_u32_e32 v15, 0x5b, v14
	v_add_u32_e32 v14, 0x7b, v14
	s_or_b64 s[66:67], s[66:67], s[68:69]
	v_cmp_lt_i32_e64 s[72:73], v14, v249
	v_cmp_gt_i32_e64 s[74:75], v14, v204
	v_cndmask_b32_e64 v112, v112, v222, s[8:9]
	v_cmp_lt_i32_e64 s[8:9], v250, v249
	v_cndmask_b32_e64 v126, v126, v222, s[66:67]
	v_cmp_lt_i32_e64 s[66:67], v15, v249
	v_cmp_gt_i32_e64 s[68:69], v15, v204
	s_or_b64 s[74:75], s[72:73], s[74:75]
	s_and_saveexec_b64 s[72:73], s[74:75]
	s_mov_b32 s74, 0xf149f2ca
	v_mov_b32_e32 v127, s74
	s_or_b64 exec, exec, s[72:73]
	s_or_b64 vcc, vcc, s[6:7]
	v_cndmask_b32_e32 v128, v128, v222, vcc
	s_or_b64 vcc, s[10:11], s[8:9]
	v_cndmask_b32_e32 v129, v129, v222, vcc
	s_or_b64 vcc, s[12:13], s[14:15]
	v_cndmask_b32_e32 v130, v130, v222, vcc
	s_or_b64 vcc, s[16:17], s[18:19]
	v_cndmask_b32_e32 v131, v131, v222, vcc
	s_or_b64 vcc, s[20:21], s[22:23]
	v_cndmask_b32_e32 v132, v132, v222, vcc
	s_or_b64 vcc, s[24:25], s[26:27]
	v_cndmask_b32_e32 v133, v133, v222, vcc
	s_or_b64 vcc, s[28:29], s[30:31]
	v_cndmask_b32_e32 v134, v134, v222, vcc
	s_or_b64 vcc, s[34:35], s[36:37]
	v_cndmask_b32_e32 v135, v135, v222, vcc
	s_or_b64 vcc, s[38:39], s[40:41]
	v_cndmask_b32_e32 v136, v136, v222, vcc
	s_or_b64 vcc, s[42:43], s[44:45]
	v_cndmask_b32_e32 v137, v137, v222, vcc
	s_or_b64 vcc, s[46:47], s[48:49]
	v_cndmask_b32_e32 v138, v138, v222, vcc
	s_or_b64 vcc, s[50:51], s[52:53]
	v_cndmask_b32_e32 v139, v139, v222, vcc
	s_or_b64 vcc, s[54:55], s[56:57]
	v_cndmask_b32_e32 v140, v140, v222, vcc
	s_or_b64 vcc, s[58:59], s[60:61]
	v_cndmask_b32_e32 v141, v141, v222, vcc
	s_or_b64 vcc, s[62:63], s[64:65]
	v_cndmask_b32_e32 v142, v142, v222, vcc
	s_or_b64 vcc, s[66:67], s[68:69]
	v_cndmask_b32_e32 v143, v143, v222, vcc
	s_mov_b32 s74, 0xc2fc0000
	s_branch .LBB0_1024
; DI float fast_exp2(float x) { return __builtin_amdgcn_exp2f(x); }
; DI float soft_update(Soft& f, f32x16& x0, f32x16& x1, bool hasO) {
;     ...
;     if (__builtin_amdgcn_ballot_w64(need)) {
;         const float delta = need ? fmaxf(mx, -60.f) : 0.f; const float sc = fast_exp2(-delta);
;         dmove = delta;
;         f.mref += delta; f.l *= sc;
;         if (hasO) {
; #pragma unroll
;             for (int r = 0; r < 16; ++r) { f.o0[r] *= sc; f.o1[r] *= sc; } }
; #pragma unroll
;         for (int r = 0; r < 16; ++r) { x0[r] -= delta; x1[r] -= delta; }
;     }
.Lwin_resc:
	v_max_f32_e32 v14, v14, v14
	v_max_f32_e32 v14, 0xc2700000, v14
	v_cndmask_b32_e64 v14, 0, v14, s[8:9]
	v_exp_f32_e64 v250, -v14
	v_add_f32_e32 v1, v1, v14
	v_pk_add_f32 v[128:129], v[128:129], v[14:15] op_sel_hi:[1,0] neg_lo:[0,1] neg_hi:[0,1]
	v_pk_add_f32 v[112:113], v[112:113], v[14:15] op_sel_hi:[1,0] neg_lo:[0,1] neg_hi:[0,1]
	v_mul_f32_e32 v210, v210, v250
	v_pk_mul_f32 v[110:111], v[110:111], v[250:251] op_sel_hi:[1,0]
	v_pk_mul_f32 v[108:109], v[108:109], v[250:251] op_sel_hi:[1,0]
	v_pk_mul_f32 v[106:107], v[106:107], v[250:251] op_sel_hi:[1,0]
	v_pk_mul_f32 v[104:105], v[104:105], v[250:251] op_sel_hi:[1,0]
	v_pk_mul_f32 v[102:103], v[102:103], v[250:251] op_sel_hi:[1,0]
	v_pk_mul_f32 v[100:101], v[100:101], v[250:251] op_sel_hi:[1,0]
	v_pk_mul_f32 v[98:99], v[98:99], v[250:251] op_sel_hi:[1,0]
	v_pk_mul_f32 v[96:97], v[96:97], v[250:251] op_sel_hi:[1,0]
	v_pk_mul_f32 v[94:95], v[94:95], v[250:251] op_sel_hi:[1,0]
	v_pk_mul_f32 v[92:93], v[92:93], v[250:251] op_sel_hi:[1,0]
	v_pk_mul_f32 v[90:91], v[90:91], v[250:251] op_sel_hi:[1,0]
	v_pk_mul_f32 v[88:89], v[88:89], v[250:251] op_sel_hi:[1,0]
	v_pk_mul_f32 v[86:87], v[86:87], v[250:251] op_sel_hi:[1,0]
	v_pk_mul_f32 v[84:85], v[84:85], v[250:251] op_sel_hi:[1,0]
	v_pk_mul_f32 v[82:83], v[82:83], v[250:251] op_sel_hi:[1,0]
	v_pk_mul_f32 v[80:81], v[80:81], v[250:251] op_sel_hi:[1,0]
	v_pk_add_f32 v[130:131], v[130:131], v[14:15] op_sel_hi:[1,0] neg_lo:[0,1] neg_hi:[0,1]
	v_pk_add_f32 v[114:115], v[114:115], v[14:15] op_sel_hi:[1,0] neg_lo:[0,1] neg_hi:[0,1]
	v_pk_add_f32 v[132:133], v[132:133], v[14:15] op_sel_hi:[1,0] neg_lo:[0,1] neg_hi:[0,1]
	v_pk_add_f32 v[116:117], v[116:117], v[14:15] op_sel_hi:[1,0] neg_lo:[0,1] neg_hi:[0,1]
	v_pk_add_f32 v[134:135], v[134:135], v[14:15] op_sel_hi:[1,0] neg_lo:[0,1] neg_hi:[0,1]
	v_pk_add_f32 v[118:119], v[118:119], v[14:15] op_sel_hi:[1,0] neg_lo:[0,1] neg_hi:[0,1]
	v_pk_add_f32 v[136:137], v[136:137], v[14:15] op_sel_hi:[1,0] neg_lo:[0,1] neg_hi:[0,1]
	v_pk_add_f32 v[120:121], v[120:121], v[14:15] op_sel_hi:[1,0] neg_lo:[0,1] neg_hi:[0,1]
	v_pk_add_f32 v[138:139], v[138:139], v[14:15] op_sel_hi:[1,0] neg_lo:[0,1] neg_hi:[0,1]
	v_pk_add_f32 v[122:123], v[122:123], v[14:15] op_sel_hi:[1,0] neg_lo:[0,1] neg_hi:[0,1]
	v_pk_add_f32 v[140:141], v[140:141], v[14:15] op_sel_hi:[1,0] neg_lo:[0,1] neg_hi:[0,1]
	v_pk_add_f32 v[124:125], v[124:125], v[14:15] op_sel_hi:[1,0] neg_lo:[0,1] neg_hi:[0,1]
	v_pk_add_f32 v[142:143], v[142:143], v[14:15] op_sel_hi:[1,0] neg_lo:[0,1] neg_hi:[0,1]
	v_pk_add_f32 v[126:127], v[126:127], v[14:15] op_sel_hi:[1,0] neg_lo:[0,1] neg_hi:[0,1]
	s_branch .LBB0_1030
